# plus: dropped the redundant lgkmcnt(0) inside the barrier block at the end of both MLA attention stage bodies
# speedup vs baseline: 1.0019x; 1.0019x over previous
.LBB0_182:
	s_or_b64 exec, exec, s[46:47]
	s_min_u32 s2, s29, 29
	s_lshl_b32 s40, s2, 7
	v_lshl_add_u64 v[62:63], v[214:215], 0, s[40:41]
	global_load_dwordx4 v[144:147], v[62:63], off offset:256
	s_waitcnt lgkmcnt(4)
	v_mfma_f32_32x32x16_bf16 v[0:15], v[48:51], v[172:175], v[0:15]
	ds_read_b128 v[80:83], v221 offset:40544
	v_max3_f32 v48, v60, v102, v70
	v_max3_f32 v48, v48, v103, v71
	v_max3_f32 v48, v48, v104, v72
	s_waitcnt lgkmcnt(3)
	v_mfma_f32_32x32x16_bf16 v[16:31], v[56:59], v[172:175], v[16:31]
	v_max3_f32 v48, v48, v105, v73
	v_max3_f32 v48, v48, v106, v74
	v_max3_f32 v48, v48, v107, v75
	s_waitcnt lgkmcnt(1)
	v_mfma_f32_32x32x16_bf16 v[0:15], v[52:55], v[168:171], v[0:15]
	v_max3_f32 v48, v48, v108, v76
	v_max3_f32 v48, v48, v109, v77
	v_max3_f32 v48, v48, v110, v78
	s_waitcnt lgkmcnt(0)
	v_mfma_f32_32x32x16_bf16 v[16:31], v[80:83], v[168:171], v[16:31]
	v_max3_f32 v48, v48, v111, v79
	s_barrier
	s_and_b64 vcc, exec, s[42:43]
	s_cbranch_vccz .LBB0_184
	s_nop 3
	v_pk_mul_f32 v[14:15], v[216:217], v[14:15] op_sel_hi:[0,1]
	v_pk_mul_f32 v[12:13], v[216:217], v[12:13] op_sel_hi:[0,1]
	v_pk_mul_f32 v[10:11], v[216:217], v[10:11] op_sel_hi:[0,1]
	v_pk_mul_f32 v[8:9], v[216:217], v[8:9] op_sel_hi:[0,1]
	v_pk_mul_f32 v[6:7], v[216:217], v[6:7] op_sel_hi:[0,1]
	v_pk_mul_f32 v[4:5], v[216:217], v[4:5] op_sel_hi:[0,1]
	v_pk_mul_f32 v[2:3], v[216:217], v[2:3] op_sel_hi:[0,1]
	v_pk_mul_f32 v[0:1], v[216:217], v[0:1] op_sel_hi:[0,1]
	v_pk_mul_f32 v[30:31], v[216:217], v[30:31] op_sel_hi:[0,1]
	v_pk_mul_f32 v[28:29], v[216:217], v[28:29] op_sel_hi:[0,1]
	v_pk_mul_f32 v[26:27], v[216:217], v[26:27] op_sel_hi:[0,1]
	v_pk_mul_f32 v[24:25], v[216:217], v[24:25] op_sel_hi:[0,1]
	v_pk_mul_f32 v[22:23], v[216:217], v[22:23] op_sel_hi:[0,1]
	v_pk_mul_f32 v[20:21], v[216:217], v[20:21] op_sel_hi:[0,1]
	v_pk_mul_f32 v[18:19], v[216:217], v[18:19] op_sel_hi:[0,1]
	v_pk_mul_f32 v[16:17], v[216:217], v[16:17] op_sel_hi:[0,1]

.LBB0_191:
	s_or_b64 exec, exec, s[46:47]
	s_min_u32 s2, s29, 28
	s_lshl_b32 s40, s2, 7
	v_lshl_add_u64 v[78:79], v[214:215], 0, s[40:41]
	global_load_dwordx4 v[156:159], v[78:79], off offset:384
	s_waitcnt lgkmcnt(4)
	v_mfma_f32_32x32x16_bf16 v[0:15], v[64:67], v[184:187], v[0:15]
	ds_read_b128 v[98:101], v221 offset:31328
	v_max3_f32 v64, v76, v86, v54
	v_max3_f32 v64, v64, v87, v55
	v_max3_f32 v64, v64, v88, v56
	s_waitcnt lgkmcnt(3)
	v_mfma_f32_32x32x16_bf16 v[16:31], v[72:75], v[184:187], v[16:31]
	v_max3_f32 v64, v64, v89, v57
	v_max3_f32 v64, v64, v90, v58
	v_max3_f32 v64, v64, v91, v59
	s_waitcnt lgkmcnt(1)
	v_mfma_f32_32x32x16_bf16 v[0:15], v[68:71], v[188:191], v[0:15]
	v_max3_f32 v64, v64, v92, v60
	v_max3_f32 v64, v64, v93, v61
	v_max3_f32 v64, v64, v94, v62
	s_waitcnt lgkmcnt(0)
	v_mfma_f32_32x32x16_bf16 v[16:31], v[98:101], v[188:191], v[16:31]
	v_max3_f32 v64, v64, v95, v63
	s_barrier
	s_and_b64 vcc, exec, s[42:43]
	s_cbranch_vccz .LBB0_193
	s_nop 3
	v_pk_mul_f32 v[14:15], v[218:219], v[14:15] op_sel_hi:[0,1]
	v_pk_mul_f32 v[12:13], v[218:219], v[12:13] op_sel_hi:[0,1]
	v_pk_mul_f32 v[10:11], v[218:219], v[10:11] op_sel_hi:[0,1]
	v_pk_mul_f32 v[8:9], v[218:219], v[8:9] op_sel_hi:[0,1]
	v_pk_mul_f32 v[6:7], v[218:219], v[6:7] op_sel_hi:[0,1]
	v_pk_mul_f32 v[4:5], v[218:219], v[4:5] op_sel_hi:[0,1]
	v_pk_mul_f32 v[2:3], v[218:219], v[2:3] op_sel_hi:[0,1]
	v_pk_mul_f32 v[0:1], v[218:219], v[0:1] op_sel_hi:[0,1]
	v_pk_mul_f32 v[30:31], v[218:219], v[30:31] op_sel_hi:[0,1]
	v_pk_mul_f32 v[28:29], v[218:219], v[28:29] op_sel_hi:[0,1]
	v_pk_mul_f32 v[26:27], v[218:219], v[26:27] op_sel_hi:[0,1]
	v_pk_mul_f32 v[24:25], v[218:219], v[24:25] op_sel_hi:[0,1]
	v_pk_mul_f32 v[22:23], v[218:219], v[22:23] op_sel_hi:[0,1]
	v_pk_mul_f32 v[20:21], v[218:219], v[20:21] op_sel_hi:[0,1]
	v_pk_mul_f32 v[18:19], v[218:219], v[18:19] op_sel_hi:[0,1]
	v_pk_mul_f32 v[16:17], v[218:219], v[16:17] op_sel_hi:[0,1]
